# attention phase: one static s_setprio 1 for waves 4-7 (younger half) for the whole phase, reset at the phase end
# baseline (speedup 1.0000x reference)
; #define ARG_IN(i) argp(i)
; __global__ void __launch_bounds__(NWAVES * 64, 2) mk_fwd(Args) {
;     ...
;                     __syncthreads();
;                     for (int uu = vcu_; uu < 256; uu += G_) { const int bh = uu >> 4, s = uu & 15, b = bh >> 3, r = bh & 7;
;     ...
;                         for (int i = 0; i < 2; ++i) { const int h = __builtin_amdgcn_readfirstlane(hmap[i ? 7 - r : r]);
;                             attn_body::attn_unit<0, 24>(b, h, i ? s : 31 - s, (const abf*)(SL + 2 * SLOT_E), (const abf*)(SL + 6 * SLOT_E), (const abf*)(SL + 7 * SLOT_E), (abf*)(SL + 2 * SLOT_E), (char*)lds_raw, (const float*)(ws + WS_CUM), (const float*)(ws + WS_BT), ARG_IN(9) + l * 256); }
;     ...
;                         for (int i = 0; i < 2; ++i)
;                             attn_body::attn_unit<1, 8>(b, r, i ? s : 31 - s, (const abf*)(SL + 0 * SLOT_E), (const abf*)(SL + 3 * SLOT_E), (const abf*)(SL + 4 * SLOT_E), (abf*)(SL + 0 * SLOT_E), (char*)lds_raw, ARG_IN(10) + (size_t)(l * 8 + r) * 257, nullptr, nullptr);
.LBB0_721:
	s_or_b64 exec, exec, s[8:9]
	s_andn2_b64 vcc, exec, s[12:13]
	s_waitcnt lgkmcnt(0)
	s_barrier
	s_cbranch_vccnz .LBB0_965
	s_add_u32 s0, s10, 0x5600000
	v_writelane_b32 v255, s0, 34
	s_addc_u32 s0, s11, 0
	v_writelane_b32 v255, s0, 35
	s_add_u32 s0, s10, 0x7600000
	v_writelane_b32 v255, s0, 36
	s_addc_u32 s0, s11, 0
	s_add_u32 s1, s10, 0xb600000
	s_addc_u32 s43, s11, 0
	s_add_u32 s59, s10, 0xc600000
	s_addc_u32 s89, s11, 0
	s_add_u32 s42, s10, 0x100000
	s_addc_u32 s82, s11, 0
	s_add_u32 s60, s10, 0x50000
	s_addc_u32 s61, s11, 0
	v_writelane_b32 v255, s1, 37
	s_add_u32 s1, s10, 0x8600000
	v_writelane_b32 v255, s1, 38
	s_addc_u32 s1, s11, 0
	v_writelane_b32 v255, s1, 39
	s_add_u32 s1, s10, 0x9600000
	v_writelane_b32 v255, s1, 40
	s_addc_u32 s1, s11, 0
	v_writelane_b32 v255, s1, 41
	s_add_u32 s1, s10, 0x101800
	v_writelane_b32 v255, s1, 42
	s_addc_u32 s1, s11, 0
	v_writelane_b32 v255, s1, 43
	v_writelane_b32 v255, s56, 44
	s_nop 1
	v_writelane_b32 v255, s57, 45
	v_readlane_b32 s1, v255, 4
	s_nop 3
	s_cmp_ge_u32 s1, 4
	s_cbranch_scc0 .Lmy_prio_done
	s_setprio 1
.Lmy_prio_done:
	s_branch .LBB0_724

; __device__ __forceinline__ unsigned xb_ld(unsigned* p)              { return __hip_atomic_load(p, __ATOMIC_RELAXED, __HIP_MEMORY_SCOPE_AGENT); }
; __device__ __forceinline__ void xcd_barrier_complete(unsigned* bar, unsigned x, unsigned& nloc, unsigned& nx) {
;     const unsigned G = gridDim.x * gridDim.y * gridDim.z;
;     unsigned sum, cnt, mine, sp = 0u;
;     for (;;) {
;         sum = 0u; cnt = 0u; mine = 0u;
; #pragma unroll
;         for (unsigned j = 0; j < 16; ++j) { const unsigned c = xb_ld(&bar[XB_XCNT(j)]); sum += c; cnt += (c > 0u) ? 1u : 0u; mine = (j == x) ? c : mine; }
; __device__ __forceinline__ void xcd_barrier(const XcdBarrier& b) {
;     asm volatile("s_waitcnt vmcnt(0)" ::: "memory");
;     __syncthreads();
;     if (threadIdx.x == 0) {
;         unsigned* bar = b.bar;
;         __builtin_amdgcn_s_waitcnt(0);
;         unsigned nloc = b.st[0], nx = b.st[1];
;         if (nloc == 0u) { xcd_barrier_complete(bar, b.x, nloc, nx); b.st[0] = nloc; b.st[1] = nx; }
.LBB0_965:
	s_setprio 0
	s_waitcnt lgkmcnt(0)
	s_load_dwordx2 s[6:7], s[96:97], 0x88
	s_waitcnt lgkmcnt(0)
	s_getreg_b32 s0, hwreg(HW_REG_XCC_ID, 0, 4)
	s_waitcnt vmcnt(0)
	v_readlane_b32 s2, v255, 2
	v_readlane_b32 s3, v255, 3
	s_barrier
	s_and_saveexec_b64 s[4:5], s[2:3]
	v_readlane_b32 s2, v255, 14
	v_readlane_b32 s71, v255, 15
	s_mov_b32 s76, 0x3f2aaaab
	s_mov_b32 s81, 0x3f317218
	s_mov_b32 s82, 0x7f800000
	s_mov_b32 s83, 0x33800000
	s_mov_b64 s[60:61], 0x1000
	s_cbranch_execz .LBB0_1017
	v_readlane_b32 s1, v255, 10
	s_waitcnt vmcnt(0) expcnt(0) lgkmcnt(0)
	s_and_b32 s0, s0, 15
	v_mov_b32_e32 v0, s1
	ds_read_b32 v3, v0
	v_readlane_b32 s1, v255, 11
	s_waitcnt lgkmcnt(0)
	v_cmp_ne_u32_e32 vcc, 0, v3
	v_mov_b32_e32 v0, s1
	ds_read_b32 v2, v0
	s_cbranch_vccnz .LBB0_981
	s_add_u32 s8, s6, 0x180200
	s_addc_u32 s9, s7, 0
	s_add_u32 s10, s6, 0x180400
	s_addc_u32 s11, s7, 0
	s_add_u32 s12, s6, 0x180500
	s_addc_u32 s13, s7, 0
	s_add_u32 s14, s6, 0x180600
	s_addc_u32 s15, s7, 0
	s_add_u32 s16, s6, 0x180700
	s_addc_u32 s17, s7, 0
	s_add_u32 s18, s6, 0x180800
	s_addc_u32 s19, s7, 0
	s_add_u32 s20, s6, 0x180900
	s_addc_u32 s21, s7, 0
	s_add_u32 s22, s6, 0x180a00
	s_addc_u32 s23, s7, 0
	s_add_u32 s24, s6, 0x180b00
	s_addc_u32 s25, s7, 0
	s_add_u32 s26, s6, 0x180c00
	s_addc_u32 s27, s7, 0
	s_add_u32 s28, s6, 0x180d00
	s_addc_u32 s29, s7, 0
	s_add_u32 s30, s6, 0x180e00
	s_addc_u32 s31, s7, 0
	s_add_u32 s34, s6, 0x180f00
	s_addc_u32 s35, s7, 0
	s_add_u32 s36, s6, 0x181000
	s_addc_u32 s37, s7, 0
	s_add_u32 s38, s6, 0x181100
	s_addc_u32 s39, s7, 0
	s_add_u32 s42, s6, 0x181200
	s_addc_u32 s43, s7, 0
	s_add_u32 s44, s6, 0x181300
	s_addc_u32 s45, s7, 0
	s_mov_b32 s1, 1
	s_branch .LBB0_969
